# v21_snake
# baseline (speedup 1.0000x reference)
; #define STAGE(P_, BASE, br, kt) do { const char* _gb = (const char*)(BASE) + (((long)(br) * K + (long)(kt) * BK) << 1); \
;     const unsigned _ld = (unsigned)(uintptr_t)(P_) + wv1024; \
;     glds16(voff0, _gb, _ld); glds16(voff1, _gb, _ld + 8192u); } while (0)
; #define LDA(dst, b, h) for (int m = 0; m < 4; ++m) for (int k = 0; k < 2; ++k) \
;     dst[m][k] = *reinterpret_cast<const bf16x8*>((char*)SA(b, h) + lds_byte(wr * 64 + m * 16 + fr, k * 32 + fq * 8))
; #define LDB(dst, b, h) for (int n = 0; n < 2; ++n) for (int k = 0; k < 2; ++k) \
;     dst[n][k] = *reinterpret_cast<const bf16x8*>((char*)SB(b, h) + lds_byte(wc * 32 + n * 16 + fr, k * 32 + fq * 8))
; #define MMA(ai, bj, At_, Bt_) do { __builtin_amdgcn_s_setprio(1); \
;     for (int m = 0; m < 4; ++m) for (int n = 0; n < 2; ++n) for (int k = 0; k < 2; ++k) \
;       acc[ai][bj][m][n] = __builtin_amdgcn_mfma_f32_16x16x32_bf16(At_[m][k], Bt_[n][k], acc[ai][bj][m][n], 0, 0, 0); \
;     __builtin_amdgcn_s_setprio(0); } while (0)
; #define WAIT_V(n) asm volatile("s_waitcnt vmcnt(" #n ")" ::: "memory")
; #define WAIT_L(n) asm volatile("s_waitcnt lgkmcnt(" #n ")" ::: "memory")
; #define BAR __builtin_amdgcn_s_barrier()
; #define SCHED __builtin_amdgcn_sched_barrier(0)
; __device__ __forceinline__ void gemm_kloop(const u16* __restrict__ A, const u16* __restrict__ Bt, const int K,
;                                            const int brow, const int bcol, f32x4 (&acc)[2][2][4][2], u16* shm, const int tidk,
;                                            const bool first) {
;     ...
;   for (int t = 0; t < nt - 2; t += 2) {
;     LDB(B0, 0, 0); SCHED; LDA(At, 0, 0); STAGE(SA(1, 1), A, brow + HALF, t + 1);
;     WAIT_L(8); BAR; WAIT_L(0); MMA(0, 0, At, B0); BAR; SCHED;
;     LDB(B1, 0, 1); STAGE(SB(0, 0), Bt, bcol, t + 2);
;     BAR; WAIT_L(0); MMA(0, 1, At, B1); BAR;
;     LDA(At, 0, 1); STAGE(SA(0, 0), A, brow, t + 2);
;     BAR; WAIT_L(0); MMA(1, 0, At, B0); BAR; SCHED;
;     STAGE(SB(0, 1), Bt, bcol + HALF, t + 2);
;     WAIT_V(6); BAR; MMA(1, 1, At, B1); BAR;
.LBB0_153:
	ds_read_b128 v[130:133], v209
	ds_read_b128 v[134:137], v209 offset:1024
	ds_read_b128 v[138:141], v209 offset:2048
	ds_read_b128 v[142:145], v209 offset:3072
	ds_read_b128 v[146:149], v210
	ds_read_b128 v[150:153], v210 offset:1024
	ds_read_b128 v[154:157], v211
	ds_read_b128 v[158:161], v211 offset:1024
	ds_read_b128 v[162:165], v212
	ds_read_b128 v[166:169], v212 offset:1024
	ds_read_b128 v[170:173], v213
	ds_read_b128 v[174:177], v213 offset:1024
	s_add_u32 s84, s15, s54
	s_addc_u32 s85, s58, s55
	s_mov_b32 s68, m0
	s_mov_b32 m0, s60
	s_nop 0
	global_load_lds_dwordx4 v207, s[84:85]
	s_mov_b32 m0, s68
	s_nop 0
	s_mov_b32 s68, m0
	s_mov_b32 m0, s57
	s_nop 0
	global_load_lds_dwordx4 v208, s[84:85]
	s_mov_b32 m0, s68
	s_waitcnt lgkmcnt(8)
	s_barrier
	s_waitcnt lgkmcnt(0)
	s_setprio 1
	s_waitcnt lgkmcnt(7)
	v_mfma_f32_16x16x32_bf16 v[126:129], v[146:149], v[130:133], v[126:129]
	v_mfma_f32_16x16x32_bf16 v[122:125], v[146:149], v[138:141], v[122:125]
	s_waitcnt lgkmcnt(5)
	v_mfma_f32_16x16x32_bf16 v[114:117], v[154:157], v[138:141], v[114:117]
	v_mfma_f32_16x16x32_bf16 v[118:121], v[154:157], v[130:133], v[118:121]
	s_waitcnt lgkmcnt(3)
	v_mfma_f32_16x16x32_bf16 v[110:113], v[162:165], v[130:133], v[110:113]
	v_mfma_f32_16x16x32_bf16 v[106:109], v[162:165], v[138:141], v[106:109]
	s_waitcnt lgkmcnt(1)
	v_mfma_f32_16x16x32_bf16 v[98:101], v[170:173], v[138:141], v[98:101]
	v_mfma_f32_16x16x32_bf16 v[102:105], v[170:173], v[130:133], v[102:105]
	v_mfma_f32_16x16x32_bf16 v[126:129], v[150:153], v[134:137], v[126:129]
	v_mfma_f32_16x16x32_bf16 v[122:125], v[150:153], v[142:145], v[122:125]
	v_mfma_f32_16x16x32_bf16 v[114:117], v[158:161], v[142:145], v[114:117]
	v_mfma_f32_16x16x32_bf16 v[118:121], v[158:161], v[134:137], v[118:121]
	v_mfma_f32_16x16x32_bf16 v[110:113], v[166:169], v[134:137], v[110:113]
	v_mfma_f32_16x16x32_bf16 v[106:109], v[166:169], v[142:145], v[106:109]
	s_waitcnt lgkmcnt(0)
	v_mfma_f32_16x16x32_bf16 v[98:101], v[174:177], v[142:145], v[98:101]
	v_mfma_f32_16x16x32_bf16 v[102:105], v[174:177], v[134:137], v[102:105]
	s_setprio 0
	s_barrier
	s_add_i32 s11, s11, 2
	ds_read_b128 v[178:181], v214
	ds_read_b128 v[182:185], v214 offset:1024
	ds_read_b128 v[218:221], v214 offset:2048
	ds_read_b128 v[222:225], v214 offset:3072
	s_add_u32 s68, s13, s54
	s_addc_u32 s93, s70, s55
	s_add_u32 s84, s68, 0x100
	s_addc_u32 s85, s93, 0
	s_mov_b32 s6, m0
	s_mov_b32 m0, s61
	s_nop 0
	global_load_lds_dwordx4 v207, s[84:85]
	s_mov_b32 m0, s6
	s_nop 0
	s_mov_b32 s6, m0
	s_mov_b32 m0, s66
	s_nop 0
	global_load_lds_dwordx4 v208, s[84:85]
	s_mov_b32 m0, s6
	s_barrier
	s_waitcnt lgkmcnt(0)
	s_setprio 1
	s_waitcnt lgkmcnt(3)
	v_mfma_f32_16x16x32_bf16 v[94:97], v[146:149], v[178:181], v[94:97]
	s_waitcnt lgkmcnt(1)
	v_mfma_f32_16x16x32_bf16 v[90:93], v[146:149], v[218:221], v[90:93]
	v_mfma_f32_16x16x32_bf16 v[82:85], v[154:157], v[218:221], v[82:85]
	v_mfma_f32_16x16x32_bf16 v[86:89], v[154:157], v[178:181], v[86:89]
	v_mfma_f32_16x16x32_bf16 v[78:81], v[162:165], v[178:181], v[78:81]
	v_mfma_f32_16x16x32_bf16 v[74:77], v[162:165], v[218:221], v[74:77]
	v_mfma_f32_16x16x32_bf16 v[66:69], v[170:173], v[218:221], v[66:69]
	v_mfma_f32_16x16x32_bf16 v[70:73], v[170:173], v[178:181], v[70:73]
	v_mfma_f32_16x16x32_bf16 v[94:97], v[150:153], v[182:185], v[94:97]
	s_waitcnt lgkmcnt(0)
	v_mfma_f32_16x16x32_bf16 v[90:93], v[150:153], v[222:225], v[90:93]
	v_mfma_f32_16x16x32_bf16 v[82:85], v[158:161], v[222:225], v[82:85]
	v_mfma_f32_16x16x32_bf16 v[86:89], v[158:161], v[182:185], v[86:89]
	v_mfma_f32_16x16x32_bf16 v[78:81], v[166:169], v[182:185], v[78:81]
	v_mfma_f32_16x16x32_bf16 v[74:77], v[166:169], v[222:225], v[74:77]
	v_mfma_f32_16x16x32_bf16 v[66:69], v[174:177], v[222:225], v[66:69]
	v_mfma_f32_16x16x32_bf16 v[70:73], v[174:177], v[182:185], v[70:73]
	s_setprio 0
	s_barrier
	ds_read_b128 v[146:149], v210 offset:16384
	ds_read_b128 v[150:153], v210 offset:17408
	ds_read_b128 v[154:157], v211 offset:16384
	ds_read_b128 v[158:161], v211 offset:17408
	ds_read_b128 v[162:165], v212 offset:16384
	ds_read_b128 v[166:169], v212 offset:17408
	ds_read_b128 v[170:173], v213 offset:16384
	ds_read_b128 v[174:177], v213 offset:17408
	s_add_u32 s6, s86, s54
	s_addc_u32 s7, s87, s55
	s_add_u32 s84, s6, 0x100
	s_addc_u32 s85, s7, 0
	s_mov_b32 s1, m0
	s_mov_b32 m0, s67
	s_nop 0
	global_load_lds_dwordx4 v207, s[84:85]
	s_mov_b32 m0, s1
	s_nop 0
	s_mov_b32 s1, m0
	s_mov_b32 m0, s78
	s_nop 0
	global_load_lds_dwordx4 v208, s[84:85]
	s_mov_b32 m0, s1
	s_barrier
	s_waitcnt lgkmcnt(0)
	s_setprio 1
	s_waitcnt lgkmcnt(7)
	v_mfma_f32_16x16x32_bf16 v[62:65], v[146:149], v[130:133], v[62:65]
	v_mfma_f32_16x16x32_bf16 v[58:61], v[146:149], v[138:141], v[58:61]
	s_waitcnt lgkmcnt(5)
	v_mfma_f32_16x16x32_bf16 v[50:53], v[154:157], v[138:141], v[50:53]
	v_mfma_f32_16x16x32_bf16 v[54:57], v[154:157], v[130:133], v[54:57]
	s_waitcnt lgkmcnt(3)
	v_mfma_f32_16x16x32_bf16 v[46:49], v[162:165], v[130:133], v[46:49]
	v_mfma_f32_16x16x32_bf16 v[42:45], v[162:165], v[138:141], v[42:45]
	s_waitcnt lgkmcnt(1)
	v_mfma_f32_16x16x32_bf16 v[34:37], v[170:173], v[138:141], v[34:37]
	v_mfma_f32_16x16x32_bf16 v[38:41], v[170:173], v[130:133], v[38:41]
	v_mfma_f32_16x16x32_bf16 v[62:65], v[150:153], v[134:137], v[62:65]
	v_mfma_f32_16x16x32_bf16 v[58:61], v[150:153], v[142:145], v[58:61]
	v_mfma_f32_16x16x32_bf16 v[50:53], v[158:161], v[142:145], v[50:53]
	v_mfma_f32_16x16x32_bf16 v[54:57], v[158:161], v[134:137], v[54:57]
	v_mfma_f32_16x16x32_bf16 v[46:49], v[166:169], v[134:137], v[46:49]
	v_mfma_f32_16x16x32_bf16 v[42:45], v[166:169], v[142:145], v[42:45]
	s_waitcnt lgkmcnt(0)
	v_mfma_f32_16x16x32_bf16 v[34:37], v[174:177], v[142:145], v[34:37]
	v_mfma_f32_16x16x32_bf16 v[38:41], v[174:177], v[134:137], v[38:41]
	s_setprio 0
	s_barrier
; #define STAGE(P_, BASE, br, kt) do { const char* _gb = (const char*)(BASE) + (((long)(br) * K + (long)(kt) * BK) << 1); \
;     const unsigned _ld = (unsigned)(uintptr_t)(P_) + wv1024; \
;     glds16(voff0, _gb, _ld); glds16(voff1, _gb, _ld + 8192u); } while (0)
; #define LDA(dst, b, h) for (int m = 0; m < 4; ++m) for (int k = 0; k < 2; ++k) \
;     dst[m][k] = *reinterpret_cast<const bf16x8*>((char*)SA(b, h) + lds_byte(wr * 64 + m * 16 + fr, k * 32 + fq * 8))
; #define LDB(dst, b, h) for (int n = 0; n < 2; ++n) for (int k = 0; k < 2; ++k) \
;     dst[n][k] = *reinterpret_cast<const bf16x8*>((char*)SB(b, h) + lds_byte(wc * 32 + n * 16 + fr, k * 32 + fq * 8))
; #define MMA(ai, bj, At_, Bt_) do { __builtin_amdgcn_s_setprio(1); \
;     for (int m = 0; m < 4; ++m) for (int n = 0; n < 2; ++n) for (int k = 0; k < 2; ++k) \
;       acc[ai][bj][m][n] = __builtin_amdgcn_mfma_f32_16x16x32_bf16(At_[m][k], Bt_[n][k], acc[ai][bj][m][n], 0, 0, 0); \
;     __builtin_amdgcn_s_setprio(0); } while (0)
; #define WAIT_V(n) asm volatile("s_waitcnt vmcnt(" #n ")" ::: "memory")
; #define WAIT_L(n) asm volatile("s_waitcnt lgkmcnt(" #n ")" ::: "memory")
; #define BAR __builtin_amdgcn_s_barrier()
; #define SCHED __builtin_amdgcn_sched_barrier(0)
; __device__ __forceinline__ void gemm_kloop(const u16* __restrict__ A, const u16* __restrict__ Bt, const int K,
;                                            const int brow, const int bcol, f32x4 (&acc)[2][2][4][2], u16* shm, const int tidk,
;                                            const bool first) {
;     ...
;     WAIT_V(6); BAR; MMA(1, 1, At, B1); BAR;
;     LDB(B0, 1, 0); SCHED; LDA(At, 1, 0); STAGE(SA(0, 1), A, brow + HALF, t + 2);
;     WAIT_L(8); BAR; WAIT_L(0); MMA(0, 0, At, B0); BAR; SCHED;
;     LDB(B1, 1, 1); STAGE(SB(1, 0), Bt, bcol, t + 3);
;     BAR; WAIT_L(0); MMA(0, 1, At, B1); BAR;
;     LDA(At, 1, 1); STAGE(SA(1, 0), A, brow, t + 3);
;     BAR; WAIT_L(0); MMA(1, 0, At, B0); BAR; SCHED;
;     STAGE(SB(1, 1), Bt, bcol + HALF, t + 3);
	s_add_u32 s1, s73, s54
	s_addc_u32 s0, s52, s55
	s_add_u32 s84, s1, 0x100
	s_addc_u32 s85, s0, 0
	s_mov_b32 s8, m0
	s_mov_b32 m0, s88
	s_nop 0
	global_load_lds_dwordx4 v207, s[84:85]
	s_mov_b32 m0, s8
	s_nop 0
	s_mov_b32 s8, m0
	s_mov_b32 m0, s92
	s_nop 0
	global_load_lds_dwordx4 v208, s[84:85]
	s_mov_b32 m0, s8
	s_waitcnt vmcnt(6)
	s_barrier
	s_setprio 1
	v_mfma_f32_16x16x32_bf16 v[30:33], v[146:149], v[178:181], v[30:33]
	v_mfma_f32_16x16x32_bf16 v[26:29], v[146:149], v[218:221], v[26:29]
	v_mfma_f32_16x16x32_bf16 v[18:21], v[154:157], v[218:221], v[18:21]
	v_mfma_f32_16x16x32_bf16 v[22:25], v[154:157], v[178:181], v[22:25]
	v_mfma_f32_16x16x32_bf16 v[14:17], v[162:165], v[178:181], v[14:17]
	v_mfma_f32_16x16x32_bf16 v[10:13], v[162:165], v[218:221], v[10:13]
	v_mfma_f32_16x16x32_bf16 v[2:5], v[170:173], v[218:221], v[2:5]
	v_mfma_f32_16x16x32_bf16 v[6:9], v[170:173], v[178:181], v[6:9]
	v_mfma_f32_16x16x32_bf16 v[30:33], v[150:153], v[182:185], v[30:33]
	v_mfma_f32_16x16x32_bf16 v[26:29], v[150:153], v[222:225], v[26:29]
	v_mfma_f32_16x16x32_bf16 v[18:21], v[158:161], v[222:225], v[18:21]
	v_mfma_f32_16x16x32_bf16 v[22:25], v[158:161], v[182:185], v[22:25]
	v_mfma_f32_16x16x32_bf16 v[14:17], v[166:169], v[182:185], v[14:17]
	v_mfma_f32_16x16x32_bf16 v[10:13], v[166:169], v[222:225], v[10:13]
	v_mfma_f32_16x16x32_bf16 v[2:5], v[174:177], v[222:225], v[2:5]
	v_mfma_f32_16x16x32_bf16 v[6:9], v[174:177], v[182:185], v[6:9]
	s_setprio 0
	s_barrier
	ds_read_b128 v[130:133], v215
	ds_read_b128 v[134:137], v215 offset:1024
	ds_read_b128 v[138:141], v215 offset:2048
	ds_read_b128 v[142:145], v215 offset:3072
	ds_read_b128 v[146:149], v210 offset:32768
	ds_read_b128 v[150:153], v210 offset:33792
	ds_read_b128 v[154:157], v211 offset:32768
	ds_read_b128 v[158:161], v211 offset:33792
	ds_read_b128 v[162:165], v212 offset:32768
	ds_read_b128 v[166:169], v212 offset:33792
	ds_read_b128 v[170:173], v213 offset:32768
	ds_read_b128 v[174:177], v213 offset:33792
	s_add_u32 s84, s71, s54
	s_addc_u32 s85, s3, s55
	s_mov_b32 s8, m0
	s_mov_b32 m0, s96
	s_nop 0
	global_load_lds_dwordx4 v207, s[84:85]
	s_mov_b32 m0, s8
	s_nop 0
	s_mov_b32 s8, m0
	s_mov_b32 m0, s97
	s_nop 0
	global_load_lds_dwordx4 v208, s[84:85]
	s_mov_b32 m0, s8
	s_waitcnt lgkmcnt(8)
	s_barrier
	s_waitcnt lgkmcnt(0)
	s_setprio 1
	s_waitcnt lgkmcnt(7)
	v_mfma_f32_16x16x32_bf16 v[126:129], v[146:149], v[130:133], v[126:129]
	v_mfma_f32_16x16x32_bf16 v[122:125], v[146:149], v[138:141], v[122:125]
	s_waitcnt lgkmcnt(5)
	v_mfma_f32_16x16x32_bf16 v[114:117], v[154:157], v[138:141], v[114:117]
	v_mfma_f32_16x16x32_bf16 v[118:121], v[154:157], v[130:133], v[118:121]
	s_waitcnt lgkmcnt(3)
	v_mfma_f32_16x16x32_bf16 v[110:113], v[162:165], v[130:133], v[110:113]
	v_mfma_f32_16x16x32_bf16 v[106:109], v[162:165], v[138:141], v[106:109]
	s_waitcnt lgkmcnt(1)
	v_mfma_f32_16x16x32_bf16 v[98:101], v[170:173], v[138:141], v[98:101]
	v_mfma_f32_16x16x32_bf16 v[102:105], v[170:173], v[130:133], v[102:105]
	v_mfma_f32_16x16x32_bf16 v[126:129], v[150:153], v[134:137], v[126:129]
	v_mfma_f32_16x16x32_bf16 v[122:125], v[150:153], v[142:145], v[122:125]
	v_mfma_f32_16x16x32_bf16 v[114:117], v[158:161], v[142:145], v[114:117]
	v_mfma_f32_16x16x32_bf16 v[118:121], v[158:161], v[134:137], v[118:121]
	v_mfma_f32_16x16x32_bf16 v[110:113], v[166:169], v[134:137], v[110:113]
	v_mfma_f32_16x16x32_bf16 v[106:109], v[166:169], v[142:145], v[106:109]
	s_waitcnt lgkmcnt(0)
	v_mfma_f32_16x16x32_bf16 v[98:101], v[174:177], v[142:145], v[98:101]
	v_mfma_f32_16x16x32_bf16 v[102:105], v[174:177], v[134:137], v[102:105]
	s_setprio 0
	s_barrier
	ds_read_b128 v[178:181], v216
	ds_read_b128 v[182:185], v216 offset:1024
	ds_read_b128 v[218:221], v216 offset:2048
	ds_read_b128 v[222:225], v216 offset:3072
	s_add_u32 s84, s68, 0x180
	s_addc_u32 s85, s93, 0
	s_mov_b32 s8, m0
	s_mov_b32 m0, s98
	s_nop 0
	global_load_lds_dwordx4 v207, s[84:85]
	s_mov_b32 m0, s8
	s_nop 0
	s_mov_b32 s8, m0
	s_mov_b32 m0, s99
	s_nop 0
	global_load_lds_dwordx4 v208, s[84:85]
	s_mov_b32 m0, s8
	s_barrier
	s_waitcnt lgkmcnt(0)
	s_setprio 1
	s_waitcnt lgkmcnt(3)
	v_mfma_f32_16x16x32_bf16 v[94:97], v[146:149], v[178:181], v[94:97]
	s_waitcnt lgkmcnt(1)
	v_mfma_f32_16x16x32_bf16 v[90:93], v[146:149], v[218:221], v[90:93]
	v_mfma_f32_16x16x32_bf16 v[82:85], v[154:157], v[218:221], v[82:85]
	v_mfma_f32_16x16x32_bf16 v[86:89], v[154:157], v[178:181], v[86:89]
	v_mfma_f32_16x16x32_bf16 v[78:81], v[162:165], v[178:181], v[78:81]
	v_mfma_f32_16x16x32_bf16 v[74:77], v[162:165], v[218:221], v[74:77]
	v_mfma_f32_16x16x32_bf16 v[66:69], v[170:173], v[218:221], v[66:69]
	v_mfma_f32_16x16x32_bf16 v[70:73], v[170:173], v[178:181], v[70:73]
	v_mfma_f32_16x16x32_bf16 v[94:97], v[150:153], v[182:185], v[94:97]
	s_waitcnt lgkmcnt(0)
	v_mfma_f32_16x16x32_bf16 v[90:93], v[150:153], v[222:225], v[90:93]
	v_mfma_f32_16x16x32_bf16 v[82:85], v[158:161], v[222:225], v[82:85]
	v_mfma_f32_16x16x32_bf16 v[86:89], v[158:161], v[182:185], v[86:89]
	v_mfma_f32_16x16x32_bf16 v[78:81], v[166:169], v[182:185], v[78:81]
	v_mfma_f32_16x16x32_bf16 v[74:77], v[166:169], v[222:225], v[74:77]
	v_mfma_f32_16x16x32_bf16 v[66:69], v[174:177], v[222:225], v[66:69]
	v_mfma_f32_16x16x32_bf16 v[70:73], v[174:177], v[182:185], v[70:73]
	s_setprio 0
	s_barrier
	ds_read_b128 v[146:149], v210 offset:49152
	ds_read_b128 v[150:153], v210 offset:50176
	ds_read_b128 v[154:157], v211 offset:49152
	ds_read_b128 v[158:161], v211 offset:50176
	ds_read_b128 v[162:165], v212 offset:49152
	ds_read_b128 v[166:169], v212 offset:50176
	ds_read_b128 v[170:173], v213 offset:49152
	ds_read_b128 v[174:177], v213 offset:50176
	s_add_u32 s84, s6, 0x180
	s_addc_u32 s85, s7, 0
	s_mov_b32 s6, m0
	s_mov_b32 m0, vcc_lo
	s_nop 0
	global_load_lds_dwordx4 v207, s[84:85]
	s_mov_b32 m0, s6
	s_nop 0
	s_mov_b32 s6, m0
	s_mov_b32 m0, vcc_hi
	s_nop 0
	global_load_lds_dwordx4 v208, s[84:85]
	s_mov_b32 m0, s6
	s_barrier
; #define STAGE(P_, BASE, br, kt) do { const char* _gb = (const char*)(BASE) + (((long)(br) * K + (long)(kt) * BK) << 1); \
;     const unsigned _ld = (unsigned)(uintptr_t)(P_) + wv1024; \
;     glds16(voff0, _gb, _ld); glds16(voff1, _gb, _ld + 8192u); } while (0)
; #define LDA(dst, b, h) for (int m = 0; m < 4; ++m) for (int k = 0; k < 2; ++k) \
;     dst[m][k] = *reinterpret_cast<const bf16x8*>((char*)SA(b, h) + lds_byte(wr * 64 + m * 16 + fr, k * 32 + fq * 8))
; #define LDB(dst, b, h) for (int n = 0; n < 2; ++n) for (int k = 0; k < 2; ++k) \
;     dst[n][k] = *reinterpret_cast<const bf16x8*>((char*)SB(b, h) + lds_byte(wc * 32 + n * 16 + fr, k * 32 + fq * 8))
; #define MMA(ai, bj, At_, Bt_) do { __builtin_amdgcn_s_setprio(1); \
;     for (int m = 0; m < 4; ++m) for (int n = 0; n < 2; ++n) for (int k = 0; k < 2; ++k) \
;       acc[ai][bj][m][n] = __builtin_amdgcn_mfma_f32_16x16x32_bf16(At_[m][k], Bt_[n][k], acc[ai][bj][m][n], 0, 0, 0); \
;     __builtin_amdgcn_s_setprio(0); } while (0)
; #define WAIT_V(n) asm volatile("s_waitcnt vmcnt(" #n ")" ::: "memory")
; #define WAIT_L(n) asm volatile("s_waitcnt lgkmcnt(" #n ")" ::: "memory")
; #define BAR __builtin_amdgcn_s_barrier()
; #define SCHED __builtin_amdgcn_sched_barrier(0)
; __device__ __forceinline__ void gemm_kloop(const u16* __restrict__ A, const u16* __restrict__ Bt, const int K,
;                                            const int brow, const int bcol, f32x4 (&acc)[2][2][4][2], u16* shm, const int tidk,
;                                            const bool first) {
;     ...
;     BAR; WAIT_L(0); MMA(1, 0, At, B0); BAR; SCHED;
;     STAGE(SB(1, 1), Bt, bcol + HALF, t + 3);
;     WAIT_V(6); BAR; MMA(1, 1, At, B1); BAR;
;     ...
;   { LDB(B0, 0, 0); LDA(At, 0, 0); STAGE(SA(1, 1), A, brow + HALF, nt - 1);
;     BAR; WAIT_L(0); MMA(0, 0, At, B0); BAR;
;     LDB(B1, 0, 1); BAR; WAIT_L(0); MMA(0, 1, At, B1); BAR;
	s_waitcnt lgkmcnt(0)
	s_setprio 1
	s_waitcnt lgkmcnt(7)
	v_mfma_f32_16x16x32_bf16 v[62:65], v[146:149], v[130:133], v[62:65]
	v_mfma_f32_16x16x32_bf16 v[58:61], v[146:149], v[138:141], v[58:61]
	s_waitcnt lgkmcnt(5)
	v_mfma_f32_16x16x32_bf16 v[50:53], v[154:157], v[138:141], v[50:53]
	v_mfma_f32_16x16x32_bf16 v[54:57], v[154:157], v[130:133], v[54:57]
	s_waitcnt lgkmcnt(3)
	v_mfma_f32_16x16x32_bf16 v[46:49], v[162:165], v[130:133], v[46:49]
	v_mfma_f32_16x16x32_bf16 v[42:45], v[162:165], v[138:141], v[42:45]
	s_waitcnt lgkmcnt(1)
	v_mfma_f32_16x16x32_bf16 v[34:37], v[170:173], v[138:141], v[34:37]
	v_mfma_f32_16x16x32_bf16 v[38:41], v[170:173], v[130:133], v[38:41]
	v_mfma_f32_16x16x32_bf16 v[62:65], v[150:153], v[134:137], v[62:65]
	v_mfma_f32_16x16x32_bf16 v[58:61], v[150:153], v[142:145], v[58:61]
	v_mfma_f32_16x16x32_bf16 v[50:53], v[158:161], v[142:145], v[50:53]
	v_mfma_f32_16x16x32_bf16 v[54:57], v[158:161], v[134:137], v[54:57]
	v_mfma_f32_16x16x32_bf16 v[46:49], v[166:169], v[134:137], v[46:49]
	v_mfma_f32_16x16x32_bf16 v[42:45], v[166:169], v[142:145], v[42:45]
	s_waitcnt lgkmcnt(0)
	v_mfma_f32_16x16x32_bf16 v[34:37], v[174:177], v[142:145], v[34:37]
	v_mfma_f32_16x16x32_bf16 v[38:41], v[174:177], v[134:137], v[38:41]
	s_setprio 0
	s_barrier
	s_add_u32 s84, s1, 0x180
	s_addc_u32 s85, s0, 0
	s_mov_b32 s0, m0
	s_mov_b32 m0, s69
	s_nop 0
	global_load_lds_dwordx4 v207, s[84:85]
	s_mov_b32 m0, s0
	s_nop 0
	s_mov_b32 s0, m0
	s_mov_b32 m0, s2
	s_nop 0
	global_load_lds_dwordx4 v208, s[84:85]
	s_mov_b32 m0, s0
	s_waitcnt vmcnt(6)
	s_barrier
	s_setprio 1
	v_mfma_f32_16x16x32_bf16 v[30:33], v[146:149], v[178:181], v[30:33]
	v_mfma_f32_16x16x32_bf16 v[26:29], v[146:149], v[218:221], v[26:29]
	v_mfma_f32_16x16x32_bf16 v[18:21], v[154:157], v[218:221], v[18:21]
	v_mfma_f32_16x16x32_bf16 v[22:25], v[154:157], v[178:181], v[22:25]
	v_mfma_f32_16x16x32_bf16 v[14:17], v[162:165], v[178:181], v[14:17]
	v_mfma_f32_16x16x32_bf16 v[10:13], v[162:165], v[218:221], v[10:13]
	v_mfma_f32_16x16x32_bf16 v[2:5], v[170:173], v[218:221], v[2:5]
	v_mfma_f32_16x16x32_bf16 v[6:9], v[170:173], v[178:181], v[6:9]
	v_mfma_f32_16x16x32_bf16 v[30:33], v[150:153], v[182:185], v[30:33]
	v_mfma_f32_16x16x32_bf16 v[26:29], v[150:153], v[222:225], v[26:29]
	v_mfma_f32_16x16x32_bf16 v[18:21], v[158:161], v[222:225], v[18:21]
	v_mfma_f32_16x16x32_bf16 v[22:25], v[158:161], v[182:185], v[22:25]
	v_mfma_f32_16x16x32_bf16 v[14:17], v[166:169], v[182:185], v[14:17]
	v_mfma_f32_16x16x32_bf16 v[10:13], v[166:169], v[222:225], v[10:13]
	v_mfma_f32_16x16x32_bf16 v[2:5], v[174:177], v[222:225], v[2:5]
	v_mfma_f32_16x16x32_bf16 v[6:9], v[174:177], v[182:185], v[6:9]
	s_setprio 0
	s_add_u32 s54, s54, 0x100
	s_addc_u32 s55, s55, 0
	s_cmp_lt_u32 s11, s64
	s_barrier
	s_cbranch_scc1 .LBB0_153
	ds_read_b128 v[130:133], v209
	ds_read_b128 v[134:137], v209 offset:1024
	ds_read_b128 v[138:141], v209 offset:2048
	ds_read_b128 v[142:145], v209 offset:3072
	ds_read_b128 v[146:149], v210
	ds_read_b128 v[150:153], v210 offset:1024
	ds_read_b128 v[154:157], v211
	ds_read_b128 v[158:161], v211 offset:1024
	ds_read_b128 v[162:165], v212
	ds_read_b128 v[166:169], v212 offset:1024
	ds_read_b128 v[170:173], v213
	ds_read_b128 v[174:177], v213 offset:1024
	s_mul_i32 s1, s56, s12
	v_readlane_b32 s2, v250, 49
	s_mul_hi_i32 s0, s56, s12
	s_add_u32 s2, s2, s1
	v_readlane_b32 s1, v250, 50
	s_addc_u32 s3, s1, s0
	s_mov_b32 s0, m0
	s_mov_b32 m0, s60
	s_nop 0
	global_load_lds_dwordx4 v207, s[2:3]
	s_mov_b32 m0, s0
	s_nop 0
	s_mov_b32 s0, m0
	s_mov_b32 m0, s57
	s_nop 0
	global_load_lds_dwordx4 v208, s[2:3]
	s_mov_b32 m0, s0
	s_barrier
	s_waitcnt lgkmcnt(0)
	s_setprio 1
	s_waitcnt lgkmcnt(7)
	v_mfma_f32_16x16x32_bf16 v[126:129], v[146:149], v[130:133], v[126:129]
	v_mfma_f32_16x16x32_bf16 v[122:125], v[146:149], v[138:141], v[122:125]
	s_waitcnt lgkmcnt(5)
	v_mfma_f32_16x16x32_bf16 v[118:121], v[154:157], v[130:133], v[118:121]
	s_waitcnt lgkmcnt(3)
	v_mfma_f32_16x16x32_bf16 v[110:113], v[162:165], v[130:133], v[110:113]
	v_mfma_f32_16x16x32_bf16 v[106:109], v[162:165], v[138:141], v[106:109]
	v_mfma_f32_16x16x32_bf16 v[126:129], v[150:153], v[134:137], v[126:129]
	v_mfma_f32_16x16x32_bf16 v[122:125], v[150:153], v[142:145], v[122:125]
	v_mfma_f32_16x16x32_bf16 v[118:121], v[158:161], v[134:137], v[118:121]
	v_mfma_f32_16x16x32_bf16 v[114:117], v[154:157], v[138:141], v[114:117]
	s_waitcnt lgkmcnt(2)
	v_mfma_f32_16x16x32_bf16 v[110:113], v[166:169], v[134:137], v[110:113]
	v_mfma_f32_16x16x32_bf16 v[106:109], v[166:169], v[142:145], v[106:109]
	s_waitcnt lgkmcnt(1)
	v_mfma_f32_16x16x32_bf16 v[102:105], v[170:173], v[130:133], v[102:105]
	v_mfma_f32_16x16x32_bf16 v[98:101], v[170:173], v[138:141], v[98:101]
	v_mfma_f32_16x16x32_bf16 v[178:181], v[158:161], v[142:145], v[114:117]
	s_waitcnt lgkmcnt(0)
	v_mfma_f32_16x16x32_bf16 v[182:185], v[174:177], v[134:137], v[102:105]
	v_mfma_f32_16x16x32_bf16 v[218:221], v[174:177], v[142:145], v[98:101]
	s_setprio 0
	s_barrier
	s_nop 1
	ds_read_b128 v[98:101], v214
	ds_read_b128 v[102:105], v214 offset:1024
	ds_read_b128 v[114:117], v214 offset:2048
	ds_read_b128 v[222:225], v214 offset:3072
	s_barrier
; #define LDA(dst, b, h) for (int m = 0; m < 4; ++m) for (int k = 0; k < 2; ++k) \
;     dst[m][k] = *reinterpret_cast<const bf16x8*>((char*)SA(b, h) + lds_byte(wr * 64 + m * 16 + fr, k * 32 + fq * 8))
; #define LDB(dst, b, h) for (int n = 0; n < 2; ++n) for (int k = 0; k < 2; ++k) \
;     dst[n][k] = *reinterpret_cast<const bf16x8*>((char*)SB(b, h) + lds_byte(wc * 32 + n * 16 + fr, k * 32 + fq * 8))
; #define MMA(ai, bj, At_, Bt_) do { __builtin_amdgcn_s_setprio(1); \
;     for (int m = 0; m < 4; ++m) for (int n = 0; n < 2; ++n) for (int k = 0; k < 2; ++k) \
;       acc[ai][bj][m][n] = __builtin_amdgcn_mfma_f32_16x16x32_bf16(At_[m][k], Bt_[n][k], acc[ai][bj][m][n], 0, 0, 0); \
;     __builtin_amdgcn_s_setprio(0); } while (0)
; #define WAIT_V(n) asm volatile("s_waitcnt vmcnt(" #n ")" ::: "memory")
; #define WAIT_L(n) asm volatile("s_waitcnt lgkmcnt(" #n ")" ::: "memory")
; #define BAR __builtin_amdgcn_s_barrier()
; __device__ __forceinline__ void gemm_kloop(const u16* __restrict__ A, const u16* __restrict__ Bt, const int K,
;                                            const int brow, const int bcol, f32x4 (&acc)[2][2][4][2], u16* shm, const int tidk,
;                                            const bool first) {
;     ...
;     LDB(B1, 0, 1); BAR; WAIT_L(0); MMA(0, 1, At, B1); BAR;
;     LDA(At, 0, 1); WAIT_V(4); BAR; WAIT_L(0); MMA(1, 0, At, B0); MMA(1, 1, At, B1); BAR; }
;   { LDB(B0, 1, 0); LDA(At, 1, 0); WAIT_V(2); BAR; WAIT_L(0); MMA(0, 0, At, B0); BAR;
;     LDB(B1, 1, 1); WAIT_V(0); BAR; WAIT_L(0); MMA(0, 1, At, B1); BAR;
	s_waitcnt lgkmcnt(0)
	s_setprio 1
	s_waitcnt lgkmcnt(3)
	v_mfma_f32_16x16x32_bf16 v[94:97], v[146:149], v[98:101], v[94:97]
	s_waitcnt lgkmcnt(1)
	v_mfma_f32_16x16x32_bf16 v[90:93], v[146:149], v[114:117], v[90:93]
	v_mfma_f32_16x16x32_bf16 v[78:81], v[162:165], v[98:101], v[78:81]
	v_mfma_f32_16x16x32_bf16 v[74:77], v[162:165], v[114:117], v[74:77]
	v_mfma_f32_16x16x32_bf16 v[70:73], v[170:173], v[98:101], v[70:73]
	v_mfma_f32_16x16x32_bf16 v[66:69], v[170:173], v[114:117], v[66:69]
	v_mfma_f32_16x16x32_bf16 v[94:97], v[150:153], v[102:105], v[94:97]
	s_waitcnt lgkmcnt(0)
	v_mfma_f32_16x16x32_bf16 v[90:93], v[150:153], v[222:225], v[90:93]
	v_mfma_f32_16x16x32_bf16 v[86:89], v[154:157], v[98:101], v[86:89]
	v_mfma_f32_16x16x32_bf16 v[82:85], v[154:157], v[114:117], v[82:85]
	v_mfma_f32_16x16x32_bf16 v[78:81], v[166:169], v[102:105], v[78:81]
	v_mfma_f32_16x16x32_bf16 v[74:77], v[166:169], v[222:225], v[74:77]
	v_mfma_f32_16x16x32_bf16 v[70:73], v[174:177], v[102:105], v[70:73]
	v_mfma_f32_16x16x32_bf16 v[66:69], v[174:177], v[222:225], v[66:69]
	v_mfma_f32_16x16x32_bf16 v[146:149], v[158:161], v[102:105], v[86:89]
	v_mfma_f32_16x16x32_bf16 v[150:153], v[158:161], v[222:225], v[82:85]
	s_setprio 0
	s_barrier
	s_nop 0
	ds_read_b128 v[82:85], v210 offset:16384
	ds_read_b128 v[86:89], v210 offset:17408
	ds_read_b128 v[154:157], v211 offset:16384
	ds_read_b128 v[158:161], v211 offset:17408
	ds_read_b128 v[162:165], v212 offset:16384
	ds_read_b128 v[166:169], v212 offset:17408
	ds_read_b128 v[170:173], v213 offset:16384
	ds_read_b128 v[174:177], v213 offset:17408
	s_waitcnt vmcnt(4)
	s_barrier
	s_waitcnt lgkmcnt(0)
	s_setprio 1
	s_waitcnt lgkmcnt(7)
	v_mfma_f32_16x16x32_bf16 v[62:65], v[82:85], v[130:133], v[62:65]
	v_mfma_f32_16x16x32_bf16 v[58:61], v[82:85], v[138:141], v[58:61]
	s_waitcnt lgkmcnt(5)
	v_mfma_f32_16x16x32_bf16 v[54:57], v[154:157], v[130:133], v[54:57]
	s_waitcnt lgkmcnt(3)
	v_mfma_f32_16x16x32_bf16 v[46:49], v[162:165], v[130:133], v[46:49]
	v_mfma_f32_16x16x32_bf16 v[42:45], v[162:165], v[138:141], v[42:45]
	v_mfma_f32_16x16x32_bf16 v[62:65], v[86:89], v[134:137], v[62:65]
	v_mfma_f32_16x16x32_bf16 v[58:61], v[86:89], v[142:145], v[58:61]
	v_mfma_f32_16x16x32_bf16 v[54:57], v[158:161], v[134:137], v[54:57]
	v_mfma_f32_16x16x32_bf16 v[50:53], v[154:157], v[138:141], v[50:53]
	s_waitcnt lgkmcnt(2)
	v_mfma_f32_16x16x32_bf16 v[46:49], v[166:169], v[134:137], v[46:49]
	v_mfma_f32_16x16x32_bf16 v[42:45], v[166:169], v[142:145], v[42:45]
	s_waitcnt lgkmcnt(1)
	v_mfma_f32_16x16x32_bf16 v[38:41], v[170:173], v[130:133], v[38:41]
	v_mfma_f32_16x16x32_bf16 v[34:37], v[170:173], v[138:141], v[34:37]
	v_mfma_f32_16x16x32_bf16 v[226:229], v[158:161], v[142:145], v[50:53]
	s_waitcnt lgkmcnt(0)
	v_mfma_f32_16x16x32_bf16 v[230:233], v[174:177], v[134:137], v[38:41]
	v_mfma_f32_16x16x32_bf16 v[234:237], v[174:177], v[142:145], v[34:37]
	s_setprio 0
	s_setprio 1
	v_mfma_f32_16x16x32_bf16 v[14:17], v[162:165], v[98:101], v[14:17]
	v_mfma_f32_16x16x32_bf16 v[10:13], v[162:165], v[114:117], v[10:13]
	v_mfma_f32_16x16x32_bf16 v[30:33], v[82:85], v[98:101], v[30:33]
	v_mfma_f32_16x16x32_bf16 v[26:29], v[82:85], v[114:117], v[26:29]
	v_mfma_f32_16x16x32_bf16 v[22:25], v[154:157], v[98:101], v[22:25]
	v_mfma_f32_16x16x32_bf16 v[18:21], v[154:157], v[114:117], v[18:21]
	v_mfma_f32_16x16x32_bf16 v[14:17], v[166:169], v[102:105], v[14:17]
	v_mfma_f32_16x16x32_bf16 v[10:13], v[166:169], v[222:225], v[10:13]
	v_mfma_f32_16x16x32_bf16 v[6:9], v[170:173], v[98:101], v[6:9]
	v_mfma_f32_16x16x32_bf16 v[2:5], v[170:173], v[114:117], v[2:5]
	v_mfma_f32_16x16x32_bf16 v[30:33], v[86:89], v[102:105], v[30:33]
	v_mfma_f32_16x16x32_bf16 v[26:29], v[86:89], v[222:225], v[26:29]
	v_mfma_f32_16x16x32_bf16 v[22:25], v[158:161], v[102:105], v[22:25]
	v_mfma_f32_16x16x32_bf16 v[18:21], v[158:161], v[222:225], v[18:21]
	v_mfma_f32_16x16x32_bf16 v[154:157], v[174:177], v[102:105], v[6:9]
	v_mfma_f32_16x16x32_bf16 v[158:161], v[174:177], v[222:225], v[2:5]
	s_setprio 0
	s_barrier
	s_nop 0
	ds_read_b128 v[2:5], v215
	ds_read_b128 v[6:9], v215 offset:1024
	ds_read_b128 v[162:165], v215 offset:2048
	ds_read_b128 v[166:169], v215 offset:3072
	ds_read_b128 v[34:37], v210 offset:32768
	ds_read_b128 v[38:41], v210 offset:33792
	ds_read_b128 v[50:53], v211 offset:32768
	ds_read_b128 v[170:173], v211 offset:33792
	ds_read_b128 v[174:177], v212 offset:32768
	ds_read_b128 v[222:225], v212 offset:33792
	ds_read_b128 v[238:241], v213 offset:32768
	ds_read_b128 v[242:245], v213 offset:33792
	s_waitcnt vmcnt(2)
	s_barrier
; #define LDA(dst, b, h) for (int m = 0; m < 4; ++m) for (int k = 0; k < 2; ++k) \
;     dst[m][k] = *reinterpret_cast<const bf16x8*>((char*)SA(b, h) + lds_byte(wr * 64 + m * 16 + fr, k * 32 + fq * 8))
; #define LDB(dst, b, h) for (int n = 0; n < 2; ++n) for (int k = 0; k < 2; ++k) \
;     dst[n][k] = *reinterpret_cast<const bf16x8*>((char*)SB(b, h) + lds_byte(wc * 32 + n * 16 + fr, k * 32 + fq * 8))
; #define MMA(ai, bj, At_, Bt_) do { __builtin_amdgcn_s_setprio(1); \
;     for (int m = 0; m < 4; ++m) for (int n = 0; n < 2; ++n) for (int k = 0; k < 2; ++k) \
;       acc[ai][bj][m][n] = __builtin_amdgcn_mfma_f32_16x16x32_bf16(At_[m][k], Bt_[n][k], acc[ai][bj][m][n], 0, 0, 0); \
;     __builtin_amdgcn_s_setprio(0); } while (0)
; #define WAIT_V(n) asm volatile("s_waitcnt vmcnt(" #n ")" ::: "memory")
; #define WAIT_L(n) asm volatile("s_waitcnt lgkmcnt(" #n ")" ::: "memory")
; #define BAR __builtin_amdgcn_s_barrier()
; __device__ __forceinline__ void gemm_kloop(const u16* __restrict__ A, const u16* __restrict__ Bt, const int K,
;                                            const int brow, const int bcol, f32x4 (&acc)[2][2][4][2], u16* shm, const int tidk,
;                                            const bool first) {
;     ...
;   { LDB(B0, 1, 0); LDA(At, 1, 0); WAIT_V(2); BAR; WAIT_L(0); MMA(0, 0, At, B0); BAR;
;     LDB(B1, 1, 1); WAIT_V(0); BAR; WAIT_L(0); MMA(0, 1, At, B1); BAR;
;     LDA(At, 1, 1); BAR; WAIT_L(0); MMA(1, 0, At, B0); MMA(1, 1, At, B1); BAR; }
;   if (wr == 0) BAR;
	s_waitcnt lgkmcnt(0)
	s_setprio 1
	s_waitcnt lgkmcnt(7)
	v_mfma_f32_16x16x32_bf16 v[82:85], v[34:37], v[2:5], v[126:129]
	s_waitcnt lgkmcnt(6)
	v_mfma_f32_16x16x32_bf16 v[130:133], v[38:41], v[6:9], v[82:85]
	v_mfma_f32_16x16x32_bf16 v[82:85], v[34:37], v[162:165], v[122:125]
	v_mfma_f32_16x16x32_bf16 v[134:137], v[38:41], v[166:169], v[82:85]
	s_waitcnt lgkmcnt(5)
	v_mfma_f32_16x16x32_bf16 v[82:85], v[50:53], v[2:5], v[118:121]
	s_waitcnt lgkmcnt(4)
	v_mfma_f32_16x16x32_bf16 v[114:117], v[170:173], v[6:9], v[82:85]
	v_mfma_f32_16x16x32_bf16 v[82:85], v[50:53], v[162:165], v[178:181]
	v_mfma_f32_16x16x32_bf16 v[118:121], v[170:173], v[166:169], v[82:85]
	s_waitcnt lgkmcnt(3)
	v_mfma_f32_16x16x32_bf16 v[82:85], v[174:177], v[2:5], v[110:113]
	s_waitcnt lgkmcnt(2)
	v_mfma_f32_16x16x32_bf16 v[98:101], v[222:225], v[6:9], v[82:85]
	v_mfma_f32_16x16x32_bf16 v[82:85], v[174:177], v[162:165], v[106:109]
	v_mfma_f32_16x16x32_bf16 v[102:105], v[222:225], v[166:169], v[82:85]
	s_waitcnt lgkmcnt(1)
	v_mfma_f32_16x16x32_bf16 v[82:85], v[238:241], v[2:5], v[182:185]
	v_mfma_f32_16x16x32_bf16 v[86:89], v[238:241], v[162:165], v[218:221]
	s_waitcnt lgkmcnt(0)
	v_mfma_f32_16x16x32_bf16 v[82:85], v[242:245], v[6:9], v[82:85]
	v_mfma_f32_16x16x32_bf16 v[86:89], v[242:245], v[166:169], v[86:89]
	s_setprio 0
	s_barrier
	ds_read_b128 v[178:181], v216
	ds_read_b128 v[182:185], v216 offset:1024
	ds_read_b128 v[218:221], v216 offset:2048
	ds_read_b128 v[246:249], v216 offset:3072
	s_waitcnt vmcnt(0)
	s_barrier
	s_waitcnt lgkmcnt(0)
	s_setprio 1
	s_waitcnt lgkmcnt(3)
	v_mfma_f32_16x16x32_bf16 v[94:97], v[34:37], v[178:181], v[94:97]
	s_waitcnt lgkmcnt(1)
	v_mfma_f32_16x16x32_bf16 v[34:37], v[34:37], v[218:221], v[90:93]
	s_waitcnt lgkmcnt(0)
	v_mfma_f32_16x16x32_bf16 v[142:145], v[38:41], v[246:249], v[34:37]
	v_mfma_f32_16x16x32_bf16 v[34:37], v[50:53], v[178:181], v[146:149]
	v_mfma_f32_16x16x32_bf16 v[122:125], v[170:173], v[182:185], v[34:37]
	v_mfma_f32_16x16x32_bf16 v[34:37], v[50:53], v[218:221], v[150:153]
	v_mfma_f32_16x16x32_bf16 v[126:129], v[170:173], v[246:249], v[34:37]
	v_mfma_f32_16x16x32_bf16 v[34:37], v[174:177], v[178:181], v[78:81]
	v_mfma_f32_16x16x32_bf16 v[106:109], v[222:225], v[182:185], v[34:37]
	v_mfma_f32_16x16x32_bf16 v[34:37], v[174:177], v[218:221], v[74:77]
	v_mfma_f32_16x16x32_bf16 v[110:113], v[222:225], v[246:249], v[34:37]
	v_mfma_f32_16x16x32_bf16 v[34:37], v[238:241], v[178:181], v[70:73]
	v_mfma_f32_16x16x32_bf16 v[90:93], v[242:245], v[182:185], v[34:37]
	v_mfma_f32_16x16x32_bf16 v[34:37], v[238:241], v[218:221], v[66:69]
	v_mfma_f32_16x16x32_bf16 v[138:141], v[38:41], v[182:185], v[94:97]
	v_mfma_f32_16x16x32_bf16 v[94:97], v[242:245], v[246:249], v[34:37]
	s_setprio 0
	s_barrier
	ds_read_b128 v[78:81], v210 offset:49152
	ds_read_b128 v[146:149], v210 offset:50176
	ds_read_b128 v[150:153], v211 offset:49152
	ds_read_b128 v[170:173], v211 offset:50176
	ds_read_b128 v[174:177], v212 offset:49152
	ds_read_b128 v[222:225], v212 offset:50176
	ds_read_b128 v[238:241], v213 offset:49152
	ds_read_b128 v[242:245], v213 offset:50176
	s_barrier
	s_waitcnt lgkmcnt(0)
	s_setprio 1
	s_waitcnt lgkmcnt(7)
	v_mfma_f32_16x16x32_bf16 v[34:37], v[78:81], v[2:5], v[62:65]
	s_waitcnt lgkmcnt(6)
	v_mfma_f32_16x16x32_bf16 v[66:69], v[146:149], v[6:9], v[34:37]
	v_mfma_f32_16x16x32_bf16 v[34:37], v[78:81], v[162:165], v[58:61]
	v_mfma_f32_16x16x32_bf16 v[70:73], v[146:149], v[166:169], v[34:37]
	s_waitcnt lgkmcnt(5)
	v_mfma_f32_16x16x32_bf16 v[34:37], v[150:153], v[2:5], v[54:57]
	s_waitcnt lgkmcnt(4)
	v_mfma_f32_16x16x32_bf16 v[50:53], v[170:173], v[6:9], v[34:37]
	v_mfma_f32_16x16x32_bf16 v[34:37], v[150:153], v[162:165], v[226:229]
	v_mfma_f32_16x16x32_bf16 v[54:57], v[170:173], v[166:169], v[34:37]
	s_waitcnt lgkmcnt(3)
	v_mfma_f32_16x16x32_bf16 v[34:37], v[174:177], v[2:5], v[46:49]
	s_waitcnt lgkmcnt(1)
	v_mfma_f32_16x16x32_bf16 v[2:5], v[238:241], v[2:5], v[230:233]
	v_mfma_f32_16x16x32_bf16 v[34:37], v[222:225], v[6:9], v[34:37]
	v_mfma_f32_16x16x32_bf16 v[38:41], v[174:177], v[162:165], v[42:45]
	s_waitcnt lgkmcnt(0)
	v_mfma_f32_16x16x32_bf16 v[2:5], v[242:245], v[6:9], v[2:5]
	v_mfma_f32_16x16x32_bf16 v[6:9], v[238:241], v[162:165], v[234:237]
	v_mfma_f32_16x16x32_bf16 v[38:41], v[222:225], v[166:169], v[38:41]
	v_mfma_f32_16x16x32_bf16 v[6:9], v[242:245], v[166:169], v[6:9]
	s_setprio 0
	s_setprio 1
	v_mfma_f32_16x16x32_bf16 v[14:17], v[174:177], v[178:181], v[14:17]
	v_mfma_f32_16x16x32_bf16 v[10:13], v[174:177], v[218:221], v[10:13]
	v_mfma_f32_16x16x32_bf16 v[30:33], v[78:81], v[178:181], v[30:33]
	v_mfma_f32_16x16x32_bf16 v[26:29], v[78:81], v[218:221], v[26:29]
	v_mfma_f32_16x16x32_bf16 v[22:25], v[150:153], v[178:181], v[22:25]
	v_mfma_f32_16x16x32_bf16 v[18:21], v[150:153], v[218:221], v[18:21]
	v_mfma_f32_16x16x32_bf16 v[42:45], v[222:225], v[182:185], v[14:17]
	v_mfma_f32_16x16x32_bf16 v[46:49], v[222:225], v[246:249], v[10:13]
	v_mfma_f32_16x16x32_bf16 v[10:13], v[238:241], v[178:181], v[154:157]
	v_mfma_f32_16x16x32_bf16 v[14:17], v[238:241], v[218:221], v[158:161]
	v_mfma_f32_16x16x32_bf16 v[74:77], v[146:149], v[182:185], v[30:33]
	v_mfma_f32_16x16x32_bf16 v[78:81], v[146:149], v[246:249], v[26:29]
	v_mfma_f32_16x16x32_bf16 v[58:61], v[170:173], v[182:185], v[22:25]
	v_mfma_f32_16x16x32_bf16 v[62:65], v[170:173], v[246:249], v[18:21]
	v_mfma_f32_16x16x32_bf16 v[10:13], v[242:245], v[182:185], v[10:13]
	v_mfma_f32_16x16x32_bf16 v[14:17], v[242:245], v[246:249], v[14:17]
	s_setprio 0
	v_readlane_b32 s0, v250, 51
	v_readlane_b32 s1, v250, 52
	s_barrier
	s_and_saveexec_b64 s[54:55], s[0:1]
	s_cbranch_execz .LBB0_156
	s_barrier
